# grid barriers: L1 invalidate issued by wave 1 right after the opening workgroup barrier (overlaps the arrival atomics and polling)
# speedup vs baseline: 1.0095x; 1.0095x over previous
; __global__ void __launch_bounds__(512, 2) hymba_fwd(Params p) {
;     ...
;     p0_prep(p, lds);
;     grid.sync();
.LBB0_62:
	s_or_b64 exec, exec, s[10:11]
	v_lshrrev_b32_e32 v1, 20, v0
	v_lshrrev_b32_e32 v0, 10, v0
	v_or_b32_e32 v0, v0, v1
	s_movk_i32 s0, 0x3ff
	v_and_or_b32 v0, v0, s0, v132
	v_cmp_eq_u32_e32 vcc, 0, v0
	s_waitcnt lgkmcnt(0)
	s_waitcnt vmcnt(0)
	s_barrier
	v_readfirstlane_b32 s97, v132
	s_cmp_eq_u32 s97, 64
	s_cbranch_scc0 .Linvw_6
	buffer_inv sc1
	s_waitcnt vmcnt(0)
.Linvw_6:
	s_and_saveexec_b64 s[0:1], vcc
	s_cbranch_execz .LBB0_72
	s_load_dwordx2 s[6:7], s[24:25], 0x58
	v_mov_b32_e32 v2, 0
	v_readlane_b32 s8, v253, 0
	v_readlane_b32 s9, v253, 1
	s_and_b32 s10, s2, 7
	s_lshl_b32 s11, s10, 7
	s_addk_i32 s11, 0x3600
	v_mov_b32_e32 v4, s11
	s_waitcnt lgkmcnt(0)
	global_load_dword v0, v2, s[6:7] offset:32 sc1
	s_nop 0
	s_waitcnt vmcnt(0)

; __global__ void __launch_bounds__(512, 2) hymba_fwd(Params p) {
;     ...
;     grid.sync();
.Lgs_inv:
	s_waitcnt vmcnt(0)
	s_nop 0
	s_waitcnt vmcnt(0)

; __device__ __forceinline__ unsigned xb_ld(unsigned* p) { return __hip_atomic_load(p, __ATOMIC_RELAXED, __HIP_MEMORY_SCOPE_AGENT); }
; __device__ __forceinline__ unsigned xb_add(unsigned* p, unsigned v) { return __hip_atomic_fetch_add(p, v, __ATOMIC_RELAXED, __HIP_MEMORY_SCOPE_AGENT); }
; __device__ __forceinline__ void xcd_barrier(const XB& b) {
;     __syncthreads();
;     if (threadIdx.x == 0) {
;         unsigned* bar = b.bar;
;         __builtin_amdgcn_fence(__ATOMIC_RELEASE, "agent");
;         asm volatile("s_waitcnt vmcnt(0)" ::: "memory");
;         const unsigned old = xb_add(&bar[XB_XSUB(b.x)], 1u);
;         const unsigned gen = old / b.nloc;
;         if (old + 1u == (gen + 1u) * b.nloc) {
;             const unsigned og = xb_add(&bar[XB_TOP], 1u);
;             const unsigned target = (og / b.nx + 1u) * b.nx;
;             if (og + 1u != target) while (xb_ld(&bar[XB_TOP]) < target) __builtin_amdgcn_s_sleep(1);
;             xb_add(&bar[XB_XGEN(b.x)], 1u);
.LBB0_94:
	s_or_b64 exec, exec, s[0:1]
	s_max_u32 s92, s3, 1
	v_max_u32_e32 v133, 1, v10
	s_waitcnt vmcnt(0) lgkmcnt(0)
	s_waitcnt vmcnt(0)
	s_barrier
	v_readfirstlane_b32 s97, v132
	s_cmp_eq_u32 s97, 64
	s_cbranch_scc0 .Linvw_5
	buffer_inv sc1
	s_waitcnt vmcnt(0)
.Linvw_5:
	s_mov_b64 s[0:1], exec
	v_readlane_b32 s6, v253, 2
	v_readlane_b32 s7, v253, 3
	s_and_b64 s[6:7], s[0:1], s[6:7]
	s_mov_b64 exec, s[6:7]
	s_cbranch_execz .LBB0_113
	s_mov_b64 s[8:9], exec
	s_nop 0
	s_waitcnt vmcnt(0)
	s_lshl_b32 s3, s89, 8
	v_readlane_b32 s6, v253, 0
	v_mbcnt_lo_u32_b32 v0, s8, 0
	v_readlane_b32 s7, v253, 1
	s_add_u32 s6, s6, s3
	v_mbcnt_hi_u32_b32 v0, s9, v0
	s_addc_u32 s7, s7, 0
	v_cmp_eq_u32_e32 vcc, 0, v0
	s_and_saveexec_b64 s[10:11], vcc
	s_cbranch_execz .LBB0_97
	s_bcnt1_i32_b64 s3, s[8:9]
	v_mov_b32_e32 v1, 0x1000
	v_mov_b32_e32 v2, s3
	global_atomic_add v1, v1, v2, s[6:7] sc0

; __device__ __forceinline__ void xcd_barrier(const XB& b) {
;     ...
;         __builtin_amdgcn_fence(__ATOMIC_ACQUIRE, "agent");
;         asm volatile("s_waitcnt vmcnt(0)" ::: "memory");
.LBB0_112:
	s_or_b64 exec, exec, s[8:9]
	s_waitcnt vmcnt(0)
	s_nop 0
	s_waitcnt vmcnt(0)

; __device__ __forceinline__ unsigned xb_ld(unsigned* p) { return __hip_atomic_load(p, __ATOMIC_RELAXED, __HIP_MEMORY_SCOPE_AGENT); }
; __device__ __forceinline__ unsigned xb_add(unsigned* p, unsigned v) { return __hip_atomic_fetch_add(p, v, __ATOMIC_RELAXED, __HIP_MEMORY_SCOPE_AGENT); }
; __device__ __forceinline__ void xcd_barrier(const XB& b) {
;     __syncthreads();
;     if (threadIdx.x == 0) {
;         unsigned* bar = b.bar;
;         __builtin_amdgcn_fence(__ATOMIC_RELEASE, "agent");
;         asm volatile("s_waitcnt vmcnt(0)" ::: "memory");
;         const unsigned old = xb_add(&bar[XB_XSUB(b.x)], 1u);
;         const unsigned gen = old / b.nloc;
;         if (old + 1u == (gen + 1u) * b.nloc) {
;             const unsigned og = xb_add(&bar[XB_TOP], 1u);
;             const unsigned target = (og / b.nx + 1u) * b.nx;
;             if (og + 1u != target) while (xb_ld(&bar[XB_TOP]) < target) __builtin_amdgcn_s_sleep(1);
;             xb_add(&bar[XB_XGEN(b.x)], 1u);
.LBB0_289:
	s_waitcnt vmcnt(0)
	s_barrier
	v_readfirstlane_b32 s97, v132
	s_cmp_eq_u32 s97, 64
	s_cbranch_scc0 .Linvw_4
	buffer_inv sc1
	s_waitcnt vmcnt(0)
.Linvw_4:
	s_mov_b64 s[0:1], exec
	v_readlane_b32 s4, v253, 2
	v_readlane_b32 s5, v253, 3
	s_and_b64 s[4:5], s[0:1], s[4:5]
	s_mov_b64 exec, s[4:5]
	s_cbranch_execz .LBB0_308
	s_mov_b64 s[6:7], exec
	buffer_wbl2 sc1
	s_waitcnt vmcnt(0)
	s_waitcnt vmcnt(0)
	s_lshl_b32 s3, s89, 8
	v_readlane_b32 s4, v253, 0
	v_mbcnt_lo_u32_b32 v0, s6, 0
	v_readlane_b32 s5, v253, 1
	s_add_u32 s4, s4, s3
	v_mbcnt_hi_u32_b32 v0, s7, v0
	s_addc_u32 s5, s5, 0
	v_cmp_eq_u32_e32 vcc, 0, v0
	s_and_saveexec_b64 s[8:9], vcc
	s_cbranch_execz .LBB0_292
	s_bcnt1_i32_b64 s3, s[6:7]
	v_mov_b32_e32 v1, 0x1000
	v_mov_b32_e32 v2, s3
	global_atomic_add v1, v1, v2, s[4:5] sc0

; __device__ __forceinline__ void xcd_barrier(const XB& b) {
;     ...
;         __builtin_amdgcn_fence(__ATOMIC_ACQUIRE, "agent");
;         asm volatile("s_waitcnt vmcnt(0)" ::: "memory");
.LBB0_307:
	s_or_b64 exec, exec, s[6:7]
	s_waitcnt vmcnt(0)
	s_nop 0
	s_waitcnt vmcnt(0)

; __device__ __forceinline__ unsigned xb_ld(unsigned* p) { return __hip_atomic_load(p, __ATOMIC_RELAXED, __HIP_MEMORY_SCOPE_AGENT); }
; __device__ __forceinline__ unsigned xb_add(unsigned* p, unsigned v) { return __hip_atomic_fetch_add(p, v, __ATOMIC_RELAXED, __HIP_MEMORY_SCOPE_AGENT); }
; __device__ __forceinline__ void xcd_barrier(const XB& b) {
;     __syncthreads();
;     if (threadIdx.x == 0) {
;         unsigned* bar = b.bar;
;         __builtin_amdgcn_fence(__ATOMIC_RELEASE, "agent");
;         asm volatile("s_waitcnt vmcnt(0)" ::: "memory");
;         const unsigned old = xb_add(&bar[XB_XSUB(b.x)], 1u);
;         const unsigned gen = old / b.nloc;
;         if (old + 1u == (gen + 1u) * b.nloc) {
;             const unsigned og = xb_add(&bar[XB_TOP], 1u);
;             const unsigned target = (og / b.nx + 1u) * b.nx;
;             if (og + 1u != target) while (xb_ld(&bar[XB_TOP]) < target) __builtin_amdgcn_s_sleep(1);
;             xb_add(&bar[XB_XGEN(b.x)], 1u);
.LBB0_363:
	s_or_b64 exec, exec, s[38:39]
	s_waitcnt vmcnt(0)
	s_barrier
	v_readfirstlane_b32 s97, v132
	s_cmp_eq_u32 s97, 64
	s_cbranch_scc0 .Linvw_3
	buffer_inv sc1
	s_waitcnt vmcnt(0)
.Linvw_3:
	s_mov_b64 s[0:1], exec
	v_readlane_b32 s4, v253, 2
	v_readlane_b32 s5, v253, 3
	s_and_b64 s[4:5], s[0:1], s[4:5]
	s_mov_b64 exec, s[4:5]
	s_cbranch_execz .LBB0_382
	s_mov_b64 s[6:7], exec
	s_nop 0
	s_waitcnt vmcnt(0)
	s_waitcnt vmcnt(0)
	s_lshl_b32 s3, s89, 8
	v_readlane_b32 s4, v253, 0
	v_mbcnt_lo_u32_b32 v0, s6, 0
	v_readlane_b32 s5, v253, 1
	s_add_u32 s4, s4, s3
	v_mbcnt_hi_u32_b32 v0, s7, v0
	s_addc_u32 s5, s5, 0
	v_cmp_eq_u32_e32 vcc, 0, v0
	s_and_saveexec_b64 s[8:9], vcc
	s_cbranch_execz .LBB0_366
	s_bcnt1_i32_b64 s3, s[6:7]
	v_mov_b32_e32 v1, 0x1000
	v_mov_b32_e32 v2, s3
	global_atomic_add v1, v1, v2, s[4:5] sc0

; __device__ __forceinline__ unsigned xb_ld(unsigned* p) { return __hip_atomic_load(p, __ATOMIC_RELAXED, __HIP_MEMORY_SCOPE_AGENT); }
; __device__ __forceinline__ unsigned xb_add(unsigned* p, unsigned v) { return __hip_atomic_fetch_add(p, v, __ATOMIC_RELAXED, __HIP_MEMORY_SCOPE_AGENT); }
; __device__ __forceinline__ void xcd_barrier(const XB& b) {
;     __syncthreads();
;     if (threadIdx.x == 0) {
;         unsigned* bar = b.bar;
;         __builtin_amdgcn_fence(__ATOMIC_RELEASE, "agent");
;         asm volatile("s_waitcnt vmcnt(0)" ::: "memory");
;         const unsigned old = xb_add(&bar[XB_XSUB(b.x)], 1u);
;         const unsigned gen = old / b.nloc;
;         if (old + 1u == (gen + 1u) * b.nloc) {
;             const unsigned og = xb_add(&bar[XB_TOP], 1u);
;             const unsigned target = (og / b.nx + 1u) * b.nx;
;             if (og + 1u != target) while (xb_ld(&bar[XB_TOP]) < target) __builtin_amdgcn_s_sleep(1);
;             xb_add(&bar[XB_XGEN(b.x)], 1u);
.LBB0_449:
	s_or_b64 exec, exec, s[0:1]
	s_waitcnt lgkmcnt(0)
	s_waitcnt vmcnt(0)
	s_barrier
	v_readfirstlane_b32 s97, v132
	s_cmp_eq_u32 s97, 64
	s_cbranch_scc0 .Linvw_2
	buffer_inv sc1
	s_waitcnt vmcnt(0)
.Linvw_2:
	s_mov_b64 s[0:1], exec
	v_readlane_b32 s6, v253, 2
	v_readlane_b32 s7, v253, 3
	s_and_b64 s[6:7], s[0:1], s[6:7]
	s_mov_b64 exec, s[6:7]
	s_cbranch_execz .LBB0_468
	s_mov_b64 s[8:9], exec
	s_nop 0
	s_waitcnt vmcnt(0)
	s_waitcnt vmcnt(0)
	s_lshl_b32 s6, s89, 8
	v_readlane_b32 s12, v253, 0
	v_mbcnt_lo_u32_b32 v0, s8, 0
	v_readlane_b32 s13, v253, 1
	s_add_u32 s6, s12, s6
	v_mbcnt_hi_u32_b32 v0, s9, v0
	s_addc_u32 s7, s13, 0
	v_cmp_eq_u32_e32 vcc, 0, v0
	s_and_saveexec_b64 s[12:13], vcc
	s_cbranch_execz .LBB0_452
	s_bcnt1_i32_b64 s8, s[8:9]
	v_mov_b32_e32 v1, 0x1000
	v_mov_b32_e32 v2, s8
	global_atomic_add v1, v1, v2, s[6:7] sc0

; __device__ __forceinline__ unsigned xb_ld(unsigned* p) { return __hip_atomic_load(p, __ATOMIC_RELAXED, __HIP_MEMORY_SCOPE_AGENT); }
; __device__ __forceinline__ unsigned xb_add(unsigned* p, unsigned v) { return __hip_atomic_fetch_add(p, v, __ATOMIC_RELAXED, __HIP_MEMORY_SCOPE_AGENT); }
; __device__ __forceinline__ void xcd_barrier(const XB& b) {
;     __syncthreads();
;     if (threadIdx.x == 0) {
;         unsigned* bar = b.bar;
;         __builtin_amdgcn_fence(__ATOMIC_RELEASE, "agent");
;         asm volatile("s_waitcnt vmcnt(0)" ::: "memory");
;         const unsigned old = xb_add(&bar[XB_XSUB(b.x)], 1u);
;         const unsigned gen = old / b.nloc;
;         if (old + 1u == (gen + 1u) * b.nloc) {
;             const unsigned og = xb_add(&bar[XB_TOP], 1u);
;             const unsigned target = (og / b.nx + 1u) * b.nx;
;             if (og + 1u != target) while (xb_ld(&bar[XB_TOP]) < target) __builtin_amdgcn_s_sleep(1);
;             xb_add(&bar[XB_XGEN(b.x)], 1u);
.LBB0_493:
	s_or_b64 exec, exec, s[6:7]
	s_waitcnt lgkmcnt(0)
	s_waitcnt vmcnt(0)
	s_barrier
	v_readfirstlane_b32 s97, v132
	s_cmp_eq_u32 s97, 64
	s_cbranch_scc0 .Linvw_1
	buffer_inv sc1
	s_waitcnt vmcnt(0)
.Linvw_1:
	s_mov_b64 s[0:1], exec
	v_readlane_b32 s6, v253, 2
	v_readlane_b32 s7, v253, 3
	s_and_b64 s[6:7], s[0:1], s[6:7]
	s_mov_b64 exec, s[6:7]
	s_cbranch_execz .LBB0_512
	s_mov_b64 s[8:9], exec
	s_nop 0
	s_waitcnt vmcnt(0)
	s_waitcnt vmcnt(0)
	s_lshl_b32 s6, s89, 8
	v_readlane_b32 s14, v253, 0
	v_mbcnt_lo_u32_b32 v0, s8, 0
	v_readlane_b32 s15, v253, 1
	s_add_u32 s6, s14, s6
	v_mbcnt_hi_u32_b32 v0, s9, v0
	s_addc_u32 s7, s15, 0
	v_cmp_eq_u32_e32 vcc, 0, v0
	s_and_saveexec_b64 s[14:15], vcc
	s_cbranch_execz .LBB0_496
	s_bcnt1_i32_b64 s8, s[8:9]
	v_mov_b32_e32 v1, 0x1000
	v_mov_b32_e32 v2, s8
	global_atomic_add v1, v1, v2, s[6:7] sc0

; __device__ __forceinline__ unsigned xb_ld(unsigned* p) { return __hip_atomic_load(p, __ATOMIC_RELAXED, __HIP_MEMORY_SCOPE_AGENT); }
; __device__ __forceinline__ unsigned xb_add(unsigned* p, unsigned v) { return __hip_atomic_fetch_add(p, v, __ATOMIC_RELAXED, __HIP_MEMORY_SCOPE_AGENT); }
; __device__ __forceinline__ void xcd_barrier(const XB& b) {
;     __syncthreads();
;     if (threadIdx.x == 0) {
;         unsigned* bar = b.bar;
;         __builtin_amdgcn_fence(__ATOMIC_RELEASE, "agent");
;         asm volatile("s_waitcnt vmcnt(0)" ::: "memory");
;         const unsigned old = xb_add(&bar[XB_XSUB(b.x)], 1u);
;         const unsigned gen = old / b.nloc;
;         if (old + 1u == (gen + 1u) * b.nloc) {
;             const unsigned og = xb_add(&bar[XB_TOP], 1u);
;             const unsigned target = (og / b.nx + 1u) * b.nx;
;             if (og + 1u != target) while (xb_ld(&bar[XB_TOP]) < target) __builtin_amdgcn_s_sleep(1);
;             xb_add(&bar[XB_XGEN(b.x)], 1u);
.LBB0_618:
	s_waitcnt lgkmcnt(0)
	s_waitcnt vmcnt(0)
	s_barrier
	v_readfirstlane_b32 s97, v132
	s_cmp_eq_u32 s97, 64
	s_cbranch_scc0 .Linvw_0
	buffer_inv sc1
	s_waitcnt vmcnt(0)
.Linvw_0:
	s_mov_b64 s[0:1], exec
	v_readlane_b32 s2, v253, 2
	v_readlane_b32 s3, v253, 3
	s_and_b64 s[2:3], s[0:1], s[2:3]
	s_mov_b64 exec, s[2:3]
	s_cbranch_execz .LBB0_637
	s_mov_b64 s[4:5], exec
	s_nop 0
	s_waitcnt vmcnt(0)
	s_waitcnt vmcnt(0)
	s_lshl_b32 s2, s89, 8
	v_readlane_b32 s6, v253, 0
	v_mbcnt_lo_u32_b32 v0, s4, 0
	v_readlane_b32 s7, v253, 1
	s_add_u32 s2, s6, s2
	v_mbcnt_hi_u32_b32 v0, s5, v0
	s_addc_u32 s3, s7, 0
	v_cmp_eq_u32_e32 vcc, 0, v0
	s_and_saveexec_b64 s[6:7], vcc
	s_cbranch_execz .LBB0_621
	s_bcnt1_i32_b64 s4, s[4:5]
	v_mov_b32_e32 v1, 0x1000
	v_mov_b32_e32 v2, s4
	global_atomic_add v1, v1, v2, s[2:3] sc0

; __device__ __forceinline__ void xcd_barrier(const XB& b) {
;     ...
;         __builtin_amdgcn_fence(__ATOMIC_ACQUIRE, "agent");
;         asm volatile("s_waitcnt vmcnt(0)" ::: "memory");
.LBB0_636:
	s_or_b64 exec, exec, s[4:5]
	s_waitcnt vmcnt(0)
	s_nop 0
	s_waitcnt vmcnt(0)
